# attention queue pull: prefetch the 8 queue counters at unit epilogue start (tid0), pull waits vmcnt(8) instead of a fresh load round trip
# baseline (speedup 1.0000x reference)
.LBB0_1974:
	s_mov_b64 s[0:1], s[70:71]
	s_load_dwordx2 s[0:1], s[0:1], 0xd0
	s_mov_b64 s[2:3], s[70:71]
	s_mov_b64 s[4:5], s[70:71]
	s_load_dwordx2 s[2:3], s[2:3], 0xd0
	s_waitcnt lgkmcnt(0)
	s_add_u32 s33, s0, 0x1b300000
	s_addc_u32 s34, s1, 0
	s_load_dwordx2 s[0:1], s[4:5], 0xd0
	s_mov_b64 s[4:5], s[70:71]
	s_load_dwordx2 s[4:5], s[4:5], 0xd0
	s_add_u32 s35, s2, 0x1f400000
	s_addc_u32 s38, s3, 0
	s_waitcnt lgkmcnt(0)
	s_add_u32 s39, s0, 0x23500000
	s_addc_u32 s40, s1, 0
	s_add_u32 s41, s4, 0x47e00000
	s_getreg_b32 s0, hwreg(HW_REG_XCC_ID, 0, 4)
	s_addc_u32 s42, s5, 0
	s_and_b32 s43, s0, 7
	s_cmp_eq_u32 s43, 1
	s_cselect_b64 s[4:5], -1, 0
	s_cmp_eq_u32 s43, 2
	s_cselect_b64 s[6:7], -1, 0
	s_cmp_eq_u32 s43, 3
	s_cselect_b64 s[8:9], -1, 0
	s_cmp_eq_u32 s43, 4
	s_cselect_b64 s[10:11], -1, 0
	s_cmp_eq_u32 s43, 5
	s_cselect_b64 s[12:13], -1, 0
	s_cmp_eq_u32 s43, 6
	s_cselect_b64 s[14:15], -1, 0
	s_cmp_eq_u32 s43, 7
	s_mov_b32 s77, s29
	v_cmp_eq_u32_e64 s[22:23], 0, v154
	s_cselect_b64 s[16:17], -1, 0
	s_mov_b64 s[86:87], s[84:85]
	s_and_saveexec_b64 s[18:19], s[22:23]
	global_load_dword v112, v1, s[36:37] offset:256 sc1
	global_load_dword v113, v1, s[36:37] offset:512 sc1
	global_load_dword v114, v1, s[36:37] offset:768 sc1
	global_load_dword v115, v1, s[36:37] offset:1024 sc1
	global_load_dword v116, v1, s[36:37] offset:1280 sc1
	global_load_dword v117, v1, s[36:37] offset:1536 sc1
	global_load_dword v118, v1, s[36:37] offset:1792 sc1
	global_load_dword v119, v1, s[36:37] offset:2048 sc1
	s_mov_b64 exec, s[18:19]
	s_waitcnt vmcnt(0)
	s_branch .LBB0_1976
.LBB0_1975:
	s_or_b64 exec, exec, s[2:3]
	s_and_saveexec_b64 s[18:19], s[22:23]
	global_load_dword v112, v1, s[36:37] offset:256 sc1
	global_load_dword v113, v1, s[36:37] offset:512 sc1
	global_load_dword v114, v1, s[36:37] offset:768 sc1
	global_load_dword v115, v1, s[36:37] offset:1024 sc1
	global_load_dword v116, v1, s[36:37] offset:1280 sc1
	global_load_dword v117, v1, s[36:37] offset:1536 sc1
	global_load_dword v118, v1, s[36:37] offset:1792 sc1
	global_load_dword v119, v1, s[36:37] offset:2048 sc1
	s_mov_b64 exec, s[18:19]
	s_waitcnt lgkmcnt(0)
	s_mul_i32 s45, s45, 0x4100000
	ds_read_b128 v[4:7], v2 offset:128
	ds_read_b128 v[8:11], v2 offset:160
	s_add_u32 s2, s41, s45
	s_addc_u32 s3, s42, 0
	s_lshl_b64 s[0:1], s[0:1], 1
	s_add_u32 s0, s2, s0
	s_addc_u32 s1, s3, s1
	s_lshl_b32 s2, s53, 1
	s_add_u32 s0, s0, s2
	s_waitcnt lgkmcnt(1)
	v_rcp_f32_e32 v12, v4
	v_rcp_f32_e32 v13, v5
	v_rcp_f32_e32 v14, v6
	v_rcp_f32_e32 v15, v7
	s_waitcnt lgkmcnt(0)
	v_rcp_f32_e32 v80, v8
	ds_read_b128 v[4:7], v2 offset:192
	v_rcp_f32_e32 v81, v9
	v_rcp_f32_e32 v82, v10
	v_rcp_f32_e32 v83, v11
	ds_read_b128 v[8:11], v2 offset:224
	s_addc_u32 s1, s1, 0
	s_lshl_b32 s2, s44, 12
	s_add_i32 s2, s2, 0
	s_add_i32 s2, s2, 0x12800
	v_lshlrev_b32_e32 v0, 9, v243
	v_lshlrev_b32_e32 v2, 1, v242
	v_add3_u32 v92, s2, v0, v2
	v_lshlrev_b32_e32 v0, 1, v244
	v_and_b32_e32 v0, 0x70, v0
	s_waitcnt lgkmcnt(0)
	v_rcp_f32_e32 v90, v10
	v_rcp_f32_e32 v91, v11
	v_add_u32_e32 v94, s2, v0
	v_lshl_add_u64 v[10:11], s[0:1], 0, v[0:1]
	v_mul_f32_e32 v0, v64, v12
	v_cvt_pk_bf16_f32 v0, v0, s0
	ds_write_b16 v92, v0
	v_mul_f32_e32 v0, v48, v12
	v_cvt_pk_bf16_f32 v0, v0, s0
	ds_write_b16 v92, v0 offset:64
	v_mul_f32_e32 v0, v65, v13
	v_cvt_pk_bf16_f32 v0, v0, s0
	ds_write_b16 v92, v0 offset:128
	v_mul_f32_e32 v0, v49, v13
	v_cvt_pk_bf16_f32 v0, v0, s0
	ds_write_b16 v92, v0 offset:192
	v_mul_f32_e32 v0, v66, v14
	v_cvt_pk_bf16_f32 v0, v0, s0
	ds_write_b16 v92, v0 offset:256
	v_mul_f32_e32 v0, v50, v14
	v_cvt_pk_bf16_f32 v0, v0, s0
	ds_write_b16 v92, v0 offset:320
	v_mul_f32_e32 v0, v67, v15
	v_cvt_pk_bf16_f32 v0, v0, s0
	ds_write_b16 v92, v0 offset:384
	v_mul_f32_e32 v0, v51, v15
	v_cvt_pk_bf16_f32 v0, v0, s0
	ds_write_b16 v92, v0 offset:448
	v_mul_f32_e32 v0, v68, v80
	v_cvt_pk_bf16_f32 v0, v0, s0
	ds_write_b16 v92, v0 offset:1024
	v_mul_f32_e32 v0, v52, v80
	v_cvt_pk_bf16_f32 v0, v0, s0
	ds_write_b16 v92, v0 offset:1088
	v_mul_f32_e32 v0, v69, v81
	v_cvt_pk_bf16_f32 v0, v0, s0
	ds_write_b16 v92, v0 offset:1152
	v_mul_f32_e32 v0, v53, v81
	v_cvt_pk_bf16_f32 v0, v0, s0
	ds_write_b16 v92, v0 offset:1216
	v_mul_f32_e32 v0, v70, v82
	v_cvt_pk_bf16_f32 v0, v0, s0
	ds_write_b16 v92, v0 offset:1280
	v_mul_f32_e32 v0, v54, v82
	v_cvt_pk_bf16_f32 v0, v0, s0
	v_rcp_f32_e32 v84, v4
	ds_write_b16 v92, v0 offset:1344
	v_mul_f32_e32 v0, v71, v83
	v_cvt_pk_bf16_f32 v0, v0, s0
	ds_write_b16 v92, v0 offset:1408
	v_mul_f32_e32 v0, v55, v83
	v_cvt_pk_bf16_f32 v0, v0, s0
	v_rcp_f32_e32 v85, v5
	ds_write_b16 v92, v0 offset:1472
	v_mul_f32_e32 v0, v72, v84
	v_cvt_pk_bf16_f32 v0, v0, s0
	ds_write_b16 v92, v0 offset:2048
	v_mul_f32_e32 v0, v56, v84
	v_cvt_pk_bf16_f32 v0, v0, s0
	v_rcp_f32_e32 v86, v6
	ds_write_b16 v92, v0 offset:2112
	v_mul_f32_e32 v0, v73, v85
	v_cvt_pk_bf16_f32 v0, v0, s0
	ds_write_b16 v92, v0 offset:2176
	v_mul_f32_e32 v0, v57, v85
	v_cvt_pk_bf16_f32 v0, v0, s0
	v_rcp_f32_e32 v87, v7
	ds_write_b16 v92, v0 offset:2240
	v_mul_f32_e32 v0, v74, v86
	v_cvt_pk_bf16_f32 v0, v0, s0
	ds_write_b16 v92, v0 offset:2304
	v_mul_f32_e32 v0, v58, v86
	v_cvt_pk_bf16_f32 v0, v0, s0
	v_rcp_f32_e32 v88, v8
	ds_write_b16 v92, v0 offset:2368
	v_mul_f32_e32 v0, v75, v87
	v_cvt_pk_bf16_f32 v0, v0, s0
	ds_write_b16 v92, v0 offset:2432
	v_mul_f32_e32 v0, v59, v87
	v_cvt_pk_bf16_f32 v0, v0, s0
	v_rcp_f32_e32 v89, v9
	ds_write_b16 v92, v0 offset:2496
	v_mul_f32_e32 v0, v76, v88
	v_cvt_pk_bf16_f32 v0, v0, s0
	ds_write_b16 v92, v0 offset:3072
	v_mul_f32_e32 v0, v60, v88
	v_cvt_pk_bf16_f32 v0, v0, s0
	ds_write_b16 v92, v0 offset:3136
	v_mul_f32_e32 v0, v77, v89
	v_cvt_pk_bf16_f32 v0, v0, s0
	ds_write_b16 v92, v0 offset:3200
	v_mul_f32_e32 v0, v61, v89
	v_cvt_pk_bf16_f32 v0, v0, s0
	ds_write_b16 v92, v0 offset:3264
	v_mul_f32_e32 v0, v78, v90
	v_cvt_pk_bf16_f32 v0, v0, s0
	ds_write_b16 v92, v0 offset:3328
	v_mul_f32_e32 v0, v62, v90
	v_cvt_pk_bf16_f32 v0, v0, s0
	ds_write_b16 v92, v0 offset:3392
	v_mul_f32_e32 v0, v79, v91
	v_cvt_pk_bf16_f32 v0, v0, s0
	ds_write_b16 v92, v0 offset:3456
	v_mul_f32_e32 v0, v63, v91
	v_lshrrev_b32_e32 v93, 3, v241
	v_cvt_pk_bf16_f32 v0, v0, s0
	ds_write_b16 v92, v0 offset:3520
	v_or_b32_e32 v50, 8, v93
	v_lshl_add_u32 v95, v93, 7, v94
	s_waitcnt lgkmcnt(0)
	v_lshl_add_u32 v56, v50, 7, v94
	ds_read_b128 v[2:5], v95
	ds_read_b128 v[6:9], v56
	v_lshlrev_b32_e32 v0, 11, v93
	v_lshl_add_u64 v[48:49], v[10:11], 0, v[0:1]
	v_lshlrev_b32_e32 v0, 11, v50
	v_lshl_add_u64 v[50:51], v[10:11], 0, v[0:1]
	v_or_b32_e32 v0, 16, v93
	v_or_b32_e32 v54, 24, v93
	v_lshl_add_u32 v57, v0, 7, v94
	v_lshl_add_u32 v58, v54, 7, v94
	s_waitcnt lgkmcnt(1)
	global_store_dwordx4 v[48:49], v[2:5], off
	ds_read_b128 v[2:5], v57
	s_waitcnt lgkmcnt(1)
	global_store_dwordx4 v[50:51], v[6:9], off
	ds_read_b128 v[6:9], v58
	v_lshlrev_b32_e32 v0, 11, v0
	v_lshl_add_u64 v[52:53], v[10:11], 0, v[0:1]
	v_lshlrev_b32_e32 v0, 11, v54
	v_lshl_add_u64 v[54:55], v[10:11], 0, v[0:1]
	v_mul_f32_e32 v0, v32, v12
	s_waitcnt lgkmcnt(1)
	global_store_dwordx4 v[52:53], v[2:5], off
	s_waitcnt lgkmcnt(0)
	global_store_dwordx4 v[54:55], v[6:9], off
	v_cvt_pk_bf16_f32 v0, v0, s0
	s_waitcnt lgkmcnt(0)
	ds_write_b16 v92, v0
	v_mul_f32_e32 v0, v16, v12
	v_cvt_pk_bf16_f32 v0, v0, s0
	ds_write_b16 v92, v0 offset:64
	v_mul_f32_e32 v0, v33, v13
	v_cvt_pk_bf16_f32 v0, v0, s0
	ds_write_b16 v92, v0 offset:128
	v_mul_f32_e32 v0, v17, v13
	v_cvt_pk_bf16_f32 v0, v0, s0
	ds_write_b16 v92, v0 offset:192
	v_mul_f32_e32 v0, v34, v14
	v_cvt_pk_bf16_f32 v0, v0, s0
	ds_write_b16 v92, v0 offset:256
	v_mul_f32_e32 v0, v18, v14
	v_cvt_pk_bf16_f32 v0, v0, s0
	ds_write_b16 v92, v0 offset:320
	v_mul_f32_e32 v0, v35, v15
	v_cvt_pk_bf16_f32 v0, v0, s0
	ds_write_b16 v92, v0 offset:384
	v_mul_f32_e32 v0, v19, v15
	v_cvt_pk_bf16_f32 v0, v0, s0
	ds_write_b16 v92, v0 offset:448
	v_mul_f32_e32 v0, v36, v80
	v_cvt_pk_bf16_f32 v0, v0, s0
	ds_write_b16 v92, v0 offset:1024
	v_mul_f32_e32 v0, v20, v80
	v_cvt_pk_bf16_f32 v0, v0, s0
	ds_write_b16 v92, v0 offset:1088
	v_mul_f32_e32 v0, v37, v81
	v_cvt_pk_bf16_f32 v0, v0, s0
	ds_write_b16 v92, v0 offset:1152
	v_mul_f32_e32 v0, v21, v81
	v_cvt_pk_bf16_f32 v0, v0, s0
	ds_write_b16 v92, v0 offset:1216
	v_mul_f32_e32 v0, v38, v82
	v_cvt_pk_bf16_f32 v0, v0, s0
	ds_write_b16 v92, v0 offset:1280
	v_mul_f32_e32 v0, v22, v82
	v_cvt_pk_bf16_f32 v0, v0, s0
	ds_write_b16 v92, v0 offset:1344
	v_mul_f32_e32 v0, v39, v83
	v_cvt_pk_bf16_f32 v0, v0, s0
	ds_write_b16 v92, v0 offset:1408
	v_mul_f32_e32 v0, v23, v83
	v_cvt_pk_bf16_f32 v0, v0, s0
	ds_write_b16 v92, v0 offset:1472
	v_mul_f32_e32 v0, v40, v84
	v_cvt_pk_bf16_f32 v0, v0, s0
	ds_write_b16 v92, v0 offset:2048
	v_mul_f32_e32 v0, v24, v84
	v_cvt_pk_bf16_f32 v0, v0, s0
	ds_write_b16 v92, v0 offset:2112
	v_mul_f32_e32 v0, v41, v85
	v_cvt_pk_bf16_f32 v0, v0, s0
	ds_write_b16 v92, v0 offset:2176
	v_mul_f32_e32 v0, v25, v85
	v_cvt_pk_bf16_f32 v0, v0, s0
	ds_write_b16 v92, v0 offset:2240
	v_mul_f32_e32 v0, v42, v86
	v_cvt_pk_bf16_f32 v0, v0, s0
	ds_write_b16 v92, v0 offset:2304
	v_mul_f32_e32 v0, v26, v86
	v_cvt_pk_bf16_f32 v0, v0, s0
	ds_write_b16 v92, v0 offset:2368
	v_mul_f32_e32 v0, v43, v87
	v_cvt_pk_bf16_f32 v0, v0, s0
	ds_write_b16 v92, v0 offset:2432
	v_mul_f32_e32 v0, v27, v87
	v_cvt_pk_bf16_f32 v0, v0, s0
	ds_write_b16 v92, v0 offset:2496
	v_mul_f32_e32 v0, v44, v88
	v_cvt_pk_bf16_f32 v0, v0, s0
	ds_write_b16 v92, v0 offset:3072
	v_mul_f32_e32 v0, v28, v88
	v_cvt_pk_bf16_f32 v0, v0, s0
	ds_write_b16 v92, v0 offset:3136
	v_mul_f32_e32 v0, v45, v89
	v_cvt_pk_bf16_f32 v0, v0, s0
	ds_write_b16 v92, v0 offset:3200
	v_mul_f32_e32 v0, v29, v89
	v_cvt_pk_bf16_f32 v0, v0, s0
	ds_write_b16 v92, v0 offset:3264
	v_mul_f32_e32 v0, v46, v90
	v_cvt_pk_bf16_f32 v0, v0, s0
	ds_write_b16 v92, v0 offset:3328
	v_mul_f32_e32 v0, v30, v90
	v_cvt_pk_bf16_f32 v0, v0, s0
	ds_write_b16 v92, v0 offset:3392
	v_mul_f32_e32 v0, v47, v91
	v_cvt_pk_bf16_f32 v0, v0, s0
	ds_write_b16 v92, v0 offset:3456
	v_mul_f32_e32 v0, v31, v91
	v_cvt_pk_bf16_f32 v0, v0, s0
	ds_write_b16 v92, v0 offset:3520
	s_waitcnt lgkmcnt(0)
	ds_read_b128 v[2:5], v95
	ds_read_b128 v[6:9], v56
	ds_read_b128 v[10:13], v57
	ds_read_b128 v[14:17], v58
	s_waitcnt lgkmcnt(3)
	global_store_dwordx4 v[48:49], v[2:5], off offset:128
	s_waitcnt lgkmcnt(2)
	global_store_dwordx4 v[50:51], v[6:9], off offset:128
	s_waitcnt lgkmcnt(1)
	global_store_dwordx4 v[52:53], v[10:13], off offset:128
	s_waitcnt lgkmcnt(0)
	global_store_dwordx4 v[54:55], v[14:17], off offset:128
	s_waitcnt lgkmcnt(0)
	s_waitcnt lgkmcnt(0)
	s_barrier
.LBB0_1976:
	s_and_saveexec_b64 s[0:1], s[22:23]
	s_cbranch_execz .LBB0_1984
	v_mov_b32_e32 v2, -1
	s_mov_b64 s[2:3], 0
	v_mov_b32_e32 v3, 15
	s_mov_b64 s[18:19], -1
	s_waitcnt vmcnt(8)
	v_mov_b32_e32 v0, v112
	v_mov_b32_e32 v4, v113
	v_mov_b32_e32 v5, v114
	v_mov_b32_e32 v6, v115
	v_mov_b32_e32 v7, v116
	v_mov_b32_e32 v8, v117
	v_mov_b32_e32 v9, v118
	v_mov_b32_e32 v10, v119
	s_branch .Lpull_common

.Lpull_common:
	v_min_u32_e32 v17, v4, v0
	v_min_u32_e32 v16, v5, v17
	v_min_u32_e32 v15, v6, v16
	v_min_u32_e32 v14, v7, v15
	v_min_u32_e32 v13, v8, v14
	v_min_u32_e32 v12, v9, v13
	v_min_u32_e32 v11, v10, v12
	v_cmp_lt_u32_e32 vcc, s55, v11
	s_cbranch_vccnz .LBB0_1979
	v_cmp_lt_u32_e32 vcc, v4, v0
	v_cndmask_b32_e64 v0, v0, v4, s[4:5]
	v_cndmask_b32_e64 v0, v0, v5, s[6:7]
	v_cndmask_b32_e64 v18, 0, 1, vcc
	v_cmp_ge_u32_e32 vcc, v5, v17
	v_cndmask_b32_e64 v0, v0, v6, s[8:9]
	v_cndmask_b32_e64 v0, v0, v7, s[10:11]
	v_cndmask_b32_e32 v17, 2, v18, vcc
	v_cmp_ge_u32_e32 vcc, v6, v16
	v_cndmask_b32_e64 v0, v0, v8, s[12:13]
	v_cndmask_b32_e64 v0, v0, v9, s[14:15]
	v_cndmask_b32_e32 v16, 3, v17, vcc
	v_cmp_ge_u32_e32 vcc, v7, v15
	v_add_u32_e32 v4, 6, v11
	s_mov_b64 s[18:19], exec
	v_cndmask_b32_e32 v15, 4, v16, vcc
	v_cmp_ge_u32_e32 vcc, v8, v14
	v_cndmask_b32_e64 v0, v0, v10, s[16:17]
	v_min_u32_e32 v4, 0xff, v4
	v_cndmask_b32_e32 v14, 5, v15, vcc
	v_cmp_ge_u32_e32 vcc, v9, v13
	v_mov_b32_e32 v5, s43
	s_nop 0
	v_cndmask_b32_e32 v13, 6, v14, vcc
	v_cmp_ge_u32_e32 vcc, v10, v12
	s_nop 1
	v_cndmask_b32_e32 v12, 7, v13, vcc
	v_cmp_lt_u32_e32 vcc, v4, v0
	v_mbcnt_lo_u32_b32 v0, s18, 0
	s_nop 0
	v_cndmask_b32_e32 v4, v5, v12, vcc
	v_mbcnt_hi_u32_b32 v5, s19, v0
	v_cmp_eq_u32_e32 vcc, 0, v5
	s_and_saveexec_b64 s[20:21], vcc
	s_cbranch_execz .LBB0_1978
	v_lshlrev_b32_e32 v0, 6, v4
	v_lshlrev_b64 v[6:7], 2, v[0:1]
	s_bcnt1_i32_b64 s18, s[18:19]
	v_lshl_add_u64 v[6:7], s[36:37], 0, v[6:7]
	v_mov_b32_e32 v0, s18
	global_atomic_add v0, v[6:7], v0, off offset:256 sc0
	s_branch .LBB0_1978
